# agent-scope (write-through) final output stores in P12 so the end-of-kernel L2 write-back has little left
# speedup vs baseline: 1.0045x; 1.0003x over previous
;     __device__ __forceinline__ void operator()(const f32x4 (&acc)[2][2][4][2], const pg8::Unit& u, int wr, int wc, int fr, int fq) const {
;         const int row0 = u.pm * 256 + wr * 64 + fr; const float* gp = gate + (size_t)(u.pm >> 5) * NMOD;
; #pragma unroll
;         for (int bj = 0; bj < 2; ++bj) {
;             const int col = u.pn * 256 + bj * 128 + wc * 32 + 8 * fq;
;             const f32x4 g0 = *(const f32x4*)(gp + col) * coef, g1 = *(const f32x4*)(gp + col + 4) * coef;
; #pragma unroll
;             for (int ai = 0; ai < 2; ++ai)
; #pragma unroll
;                 for (int m = 0; m < 4; ++m) {
;                     const size_t off = (size_t)(row0 + ai * 128 + m * 16) * DM + col;
;                     const f32x4 x0 = *(const f32x4*)(base + off), x1 = *(const f32x4*)(base + off + 4);
;                     *(f32x4*)(out + off) = x0 + g0 * acc[ai][bj][m][0]; *(f32x4*)(out + off + 4) = x1 + g1 * acc[ai][bj][m][1];
.LBB0_1396:
	v_and_b32_e32 v243, 8, v156
	v_sub_u32_e32 v240, v156, v243
	v_lshrrev_b32_e32 v243, 1, v243
	v_add_u32_e32 v241, v158, v243
	v_lshl_add_u32 v240, s47, 8, v240
	v_lshl_add_u32 v241, s48, 8, v241
	v_lshlrev_b32_e32 v240, 10, v240
	v_add_lshl_u32 v240, v240, v241, 2
	v_lshlrev_b32_e32 v241, 2, v241
	v_add_u32_e32 v242, 0x8000, v240
	s_ashr_i32 s98, s47, 5
	s_mul_i32 s98, s98, 0x9000
	s_add_u32 s98, s38, s98
	s_addc_u32 s99, s39, 0
	global_load_dwordx4 v[144:147], v241, s[98:99]
	s_add_u32 s100, s90, 0x0
	s_addc_u32 s101, s91, 0
	global_load_dwordx4 v[172:175], v240, s[100:101]
	global_load_dwordx4 v[176:179], v242, s[100:101]
	s_add_u32 s100, s90, 0x10000
	s_addc_u32 s101, s91, 0
	global_load_dwordx4 v[180:183], v240, s[100:101]
	global_load_dwordx4 v[184:187], v242, s[100:101]
	s_add_u32 s100, s90, 0x20000
	s_addc_u32 s101, s91, 0
	global_load_dwordx4 v[188:191], v240, s[100:101]
	global_load_dwordx4 v[192:195], v242, s[100:101]
	s_add_u32 s100, s90, 0x30000
	s_addc_u32 s101, s91, 0
	global_load_dwordx4 v[196:199], v240, s[100:101]
	global_load_dwordx4 v[200:203], v242, s[100:101]
	s_add_u32 s100, s90, 0x80000
	s_addc_u32 s101, s91, 0
	global_load_dwordx4 v[208:211], v240, s[100:101]
	global_load_dwordx4 v[212:215], v242, s[100:101]
	s_add_u32 s100, s90, 0x90000
	s_addc_u32 s101, s91, 0
	global_load_dwordx4 v[216:219], v240, s[100:101]
	global_load_dwordx4 v[220:223], v242, s[100:101]
	s_add_u32 s100, s90, 0xa0000
	s_addc_u32 s101, s91, 0
	global_load_dwordx4 v[224:227], v240, s[100:101]
	global_load_dwordx4 v[228:231], v242, s[100:101]
	s_add_u32 s100, s90, 0xb0000
	s_addc_u32 s101, s91, 0
	global_load_dwordx4 v[232:235], v240, s[100:101]
	global_load_dwordx4 v[236:239], v242, s[100:101]
	v_mov_b32_dpp v148, v120 row_ror:8 row_mask:0xf bank_mask:0xf
	v_mov_b32_dpp v149, v121 row_ror:8 row_mask:0xf bank_mask:0xf
	v_mov_b32_dpp v150, v122 row_ror:8 row_mask:0xf bank_mask:0xf
	v_mov_b32_dpp v151, v123 row_ror:8 row_mask:0xf bank_mask:0xf
	v_mov_b32_dpp v120, v124 row_ror:8 row_mask:0xf bank_mask:0x3
	v_mov_b32_dpp v121, v125 row_ror:8 row_mask:0xf bank_mask:0x3
	v_mov_b32_dpp v122, v126 row_ror:8 row_mask:0xf bank_mask:0x3
	v_mov_b32_dpp v123, v127 row_ror:8 row_mask:0xf bank_mask:0x3
	v_mov_b32_dpp v124, v148 quad_perm:[0,1,2,3] row_mask:0xf bank_mask:0xc
	v_mov_b32_dpp v125, v149 quad_perm:[0,1,2,3] row_mask:0xf bank_mask:0xc
	v_mov_b32_dpp v126, v150 quad_perm:[0,1,2,3] row_mask:0xf bank_mask:0xc
	v_mov_b32_dpp v127, v151 quad_perm:[0,1,2,3] row_mask:0xf bank_mask:0xc
	s_waitcnt vmcnt(16)
	v_pk_mul_f32 v[144:145], v[144:145], 0.5 op_sel_hi:[1,0]
	v_pk_mul_f32 v[146:147], v[146:147], 0.5 op_sel_hi:[1,0]
	s_waitcnt vmcnt(14)
	v_pk_fma_f32 v[124:125], v[124:125], v[144:145], v[172:173]
	v_pk_fma_f32 v[126:127], v[126:127], v[146:147], v[174:175]
	v_pk_fma_f32 v[120:121], v[120:121], v[144:145], v[176:177]
	v_pk_fma_f32 v[122:123], v[122:123], v[146:147], v[178:179]
	s_add_u32 s98, s90, 0x0
	s_addc_u32 s99, s91, 0
	global_store_dwordx4 v240, v[124:127], s[98:99] sc1
	global_store_dwordx4 v242, v[120:123], s[98:99] sc1
	s_add_u32 s100, s90, 0x0
	s_addc_u32 s101, s91, 0
	global_load_dwordx4 v[172:175], v240, s[100:101] offset:512
	global_load_dwordx4 v[176:179], v242, s[100:101] offset:512
	s_ashr_i32 s98, s47, 5
	s_mul_i32 s98, s98, 0x9000
	s_add_u32 s98, s38, s98
	s_addc_u32 s99, s39, 0
	global_load_dwordx4 v[120:123], v241, s[98:99] offset:512
	v_mov_b32_dpp v148, v112 row_ror:8 row_mask:0xf bank_mask:0xf
	v_mov_b32_dpp v149, v113 row_ror:8 row_mask:0xf bank_mask:0xf
	v_mov_b32_dpp v150, v114 row_ror:8 row_mask:0xf bank_mask:0xf
	v_mov_b32_dpp v151, v115 row_ror:8 row_mask:0xf bank_mask:0xf
	v_mov_b32_dpp v112, v116 row_ror:8 row_mask:0xf bank_mask:0x3
	v_mov_b32_dpp v113, v117 row_ror:8 row_mask:0xf bank_mask:0x3
	v_mov_b32_dpp v114, v118 row_ror:8 row_mask:0xf bank_mask:0x3
	v_mov_b32_dpp v115, v119 row_ror:8 row_mask:0xf bank_mask:0x3
	v_mov_b32_dpp v116, v148 quad_perm:[0,1,2,3] row_mask:0xf bank_mask:0xc
	v_mov_b32_dpp v117, v149 quad_perm:[0,1,2,3] row_mask:0xf bank_mask:0xc
	v_mov_b32_dpp v118, v150 quad_perm:[0,1,2,3] row_mask:0xf bank_mask:0xc
	v_mov_b32_dpp v119, v151 quad_perm:[0,1,2,3] row_mask:0xf bank_mask:0xc
	s_waitcnt vmcnt(17)
	v_pk_fma_f32 v[116:117], v[116:117], v[144:145], v[180:181]
	v_pk_fma_f32 v[118:119], v[118:119], v[146:147], v[182:183]
	v_pk_fma_f32 v[112:113], v[112:113], v[144:145], v[184:185]
	v_pk_fma_f32 v[114:115], v[114:115], v[146:147], v[186:187]
	s_add_u32 s98, s90, 0x10000
	s_addc_u32 s99, s91, 0
	global_store_dwordx4 v240, v[116:119], s[98:99] sc1
	global_store_dwordx4 v242, v[112:115], s[98:99] sc1
	s_add_u32 s100, s90, 0x10000
	s_addc_u32 s101, s91, 0
	global_load_dwordx4 v[180:183], v240, s[100:101] offset:512
	global_load_dwordx4 v[184:187], v242, s[100:101] offset:512
	v_mov_b32_dpp v148, v104 row_ror:8 row_mask:0xf bank_mask:0xf
	v_mov_b32_dpp v149, v105 row_ror:8 row_mask:0xf bank_mask:0xf
	v_mov_b32_dpp v150, v106 row_ror:8 row_mask:0xf bank_mask:0xf
	v_mov_b32_dpp v151, v107 row_ror:8 row_mask:0xf bank_mask:0xf
	v_mov_b32_dpp v104, v108 row_ror:8 row_mask:0xf bank_mask:0x3
	v_mov_b32_dpp v105, v109 row_ror:8 row_mask:0xf bank_mask:0x3
	v_mov_b32_dpp v106, v110 row_ror:8 row_mask:0xf bank_mask:0x3
	v_mov_b32_dpp v107, v111 row_ror:8 row_mask:0xf bank_mask:0x3
	v_mov_b32_dpp v108, v148 quad_perm:[0,1,2,3] row_mask:0xf bank_mask:0xc
	v_mov_b32_dpp v109, v149 quad_perm:[0,1,2,3] row_mask:0xf bank_mask:0xc
	v_mov_b32_dpp v110, v150 quad_perm:[0,1,2,3] row_mask:0xf bank_mask:0xc
	v_mov_b32_dpp v111, v151 quad_perm:[0,1,2,3] row_mask:0xf bank_mask:0xc
	s_waitcnt vmcnt(19)
;     __device__ __forceinline__ void operator()(const f32x4 (&acc)[2][2][4][2], const pg8::Unit& u, int wr, int wc, int fr, int fq) const {
;     ...
;             for (int ai = 0; ai < 2; ++ai)
; #pragma unroll
;                 for (int m = 0; m < 4; ++m) {
;                     const size_t off = (size_t)(row0 + ai * 128 + m * 16) * DM + col;
;                     const f32x4 x0 = *(const f32x4*)(base + off), x1 = *(const f32x4*)(base + off + 4);
;                     *(f32x4*)(out + off) = x0 + g0 * acc[ai][bj][m][0]; *(f32x4*)(out + off + 4) = x1 + g1 * acc[ai][bj][m][1];
;                     if (m & 1) asm volatile("" ::: "memory");
	v_pk_fma_f32 v[108:109], v[108:109], v[144:145], v[188:189]
	v_pk_fma_f32 v[110:111], v[110:111], v[146:147], v[190:191]
	v_pk_fma_f32 v[104:105], v[104:105], v[144:145], v[192:193]
	v_pk_fma_f32 v[106:107], v[106:107], v[146:147], v[194:195]
	s_add_u32 s98, s90, 0x20000
	s_addc_u32 s99, s91, 0
	global_store_dwordx4 v240, v[108:111], s[98:99] sc1
	global_store_dwordx4 v242, v[104:107], s[98:99] sc1
	s_add_u32 s100, s90, 0x20000
	s_addc_u32 s101, s91, 0
	global_load_dwordx4 v[188:191], v240, s[100:101] offset:512
	global_load_dwordx4 v[192:195], v242, s[100:101] offset:512
	v_mov_b32_dpp v148, v96 row_ror:8 row_mask:0xf bank_mask:0xf
	v_mov_b32_dpp v149, v97 row_ror:8 row_mask:0xf bank_mask:0xf
	v_mov_b32_dpp v150, v98 row_ror:8 row_mask:0xf bank_mask:0xf
	v_mov_b32_dpp v151, v99 row_ror:8 row_mask:0xf bank_mask:0xf
	v_mov_b32_dpp v96, v100 row_ror:8 row_mask:0xf bank_mask:0x3
	v_mov_b32_dpp v97, v101 row_ror:8 row_mask:0xf bank_mask:0x3
	v_mov_b32_dpp v98, v102 row_ror:8 row_mask:0xf bank_mask:0x3
	v_mov_b32_dpp v99, v103 row_ror:8 row_mask:0xf bank_mask:0x3
	v_mov_b32_dpp v100, v148 quad_perm:[0,1,2,3] row_mask:0xf bank_mask:0xc
	v_mov_b32_dpp v101, v149 quad_perm:[0,1,2,3] row_mask:0xf bank_mask:0xc
	v_mov_b32_dpp v102, v150 quad_perm:[0,1,2,3] row_mask:0xf bank_mask:0xc
	v_mov_b32_dpp v103, v151 quad_perm:[0,1,2,3] row_mask:0xf bank_mask:0xc
	s_waitcnt vmcnt(21)
	v_pk_fma_f32 v[100:101], v[100:101], v[144:145], v[196:197]
	v_pk_fma_f32 v[102:103], v[102:103], v[146:147], v[198:199]
	v_pk_fma_f32 v[96:97], v[96:97], v[144:145], v[200:201]
	v_pk_fma_f32 v[98:99], v[98:99], v[146:147], v[202:203]
	s_add_u32 s98, s90, 0x30000
	s_addc_u32 s99, s91, 0
	global_store_dwordx4 v240, v[100:103], s[98:99] sc1
	global_store_dwordx4 v242, v[96:99], s[98:99] sc1
	s_add_u32 s100, s90, 0x30000
	s_addc_u32 s101, s91, 0
	global_load_dwordx4 v[196:199], v240, s[100:101] offset:512
	global_load_dwordx4 v[200:203], v242, s[100:101] offset:512
	v_mov_b32_dpp v148, v88 row_ror:8 row_mask:0xf bank_mask:0xf
	v_mov_b32_dpp v149, v89 row_ror:8 row_mask:0xf bank_mask:0xf
	v_mov_b32_dpp v150, v90 row_ror:8 row_mask:0xf bank_mask:0xf
	v_mov_b32_dpp v151, v91 row_ror:8 row_mask:0xf bank_mask:0xf
	v_mov_b32_dpp v88, v92 row_ror:8 row_mask:0xf bank_mask:0x3
	v_mov_b32_dpp v89, v93 row_ror:8 row_mask:0xf bank_mask:0x3
	v_mov_b32_dpp v90, v94 row_ror:8 row_mask:0xf bank_mask:0x3
	v_mov_b32_dpp v91, v95 row_ror:8 row_mask:0xf bank_mask:0x3
	v_mov_b32_dpp v92, v148 quad_perm:[0,1,2,3] row_mask:0xf bank_mask:0xc
	v_mov_b32_dpp v93, v149 quad_perm:[0,1,2,3] row_mask:0xf bank_mask:0xc
	v_mov_b32_dpp v94, v150 quad_perm:[0,1,2,3] row_mask:0xf bank_mask:0xc
	v_mov_b32_dpp v95, v151 quad_perm:[0,1,2,3] row_mask:0xf bank_mask:0xc
	s_waitcnt vmcnt(23)
	v_pk_fma_f32 v[92:93], v[92:93], v[144:145], v[208:209]
	v_pk_fma_f32 v[94:95], v[94:95], v[146:147], v[210:211]
	v_pk_fma_f32 v[88:89], v[88:89], v[144:145], v[212:213]
	v_pk_fma_f32 v[90:91], v[90:91], v[146:147], v[214:215]
	s_add_u32 s98, s90, 0x80000
	s_addc_u32 s99, s91, 0
	global_store_dwordx4 v240, v[92:95], s[98:99] sc1
	global_store_dwordx4 v242, v[88:91], s[98:99] sc1
	s_add_u32 s100, s90, 0x80000
	s_addc_u32 s101, s91, 0
	global_load_dwordx4 v[208:211], v240, s[100:101] offset:512
	global_load_dwordx4 v[212:215], v242, s[100:101] offset:512
	v_mov_b32_dpp v148, v80 row_ror:8 row_mask:0xf bank_mask:0xf
	v_mov_b32_dpp v149, v81 row_ror:8 row_mask:0xf bank_mask:0xf
	v_mov_b32_dpp v150, v82 row_ror:8 row_mask:0xf bank_mask:0xf
	v_mov_b32_dpp v151, v83 row_ror:8 row_mask:0xf bank_mask:0xf
	v_mov_b32_dpp v80, v84 row_ror:8 row_mask:0xf bank_mask:0x3
	v_mov_b32_dpp v81, v85 row_ror:8 row_mask:0xf bank_mask:0x3
	v_mov_b32_dpp v82, v86 row_ror:8 row_mask:0xf bank_mask:0x3
	v_mov_b32_dpp v83, v87 row_ror:8 row_mask:0xf bank_mask:0x3
	v_mov_b32_dpp v84, v148 quad_perm:[0,1,2,3] row_mask:0xf bank_mask:0xc
	v_mov_b32_dpp v85, v149 quad_perm:[0,1,2,3] row_mask:0xf bank_mask:0xc
	v_mov_b32_dpp v86, v150 quad_perm:[0,1,2,3] row_mask:0xf bank_mask:0xc
	v_mov_b32_dpp v87, v151 quad_perm:[0,1,2,3] row_mask:0xf bank_mask:0xc
	s_waitcnt vmcnt(25)
	v_pk_fma_f32 v[84:85], v[84:85], v[144:145], v[216:217]
	v_pk_fma_f32 v[86:87], v[86:87], v[146:147], v[218:219]
	v_pk_fma_f32 v[80:81], v[80:81], v[144:145], v[220:221]
	v_pk_fma_f32 v[82:83], v[82:83], v[146:147], v[222:223]
	s_add_u32 s98, s90, 0x90000
	s_addc_u32 s99, s91, 0
	global_store_dwordx4 v240, v[84:87], s[98:99] sc1
	global_store_dwordx4 v242, v[80:83], s[98:99] sc1
	s_add_u32 s100, s90, 0x90000
	s_addc_u32 s101, s91, 0
	global_load_dwordx4 v[216:219], v240, s[100:101] offset:512
	global_load_dwordx4 v[220:223], v242, s[100:101] offset:512
	v_mov_b32_dpp v148, v72 row_ror:8 row_mask:0xf bank_mask:0xf
	v_mov_b32_dpp v149, v73 row_ror:8 row_mask:0xf bank_mask:0xf
	v_mov_b32_dpp v150, v74 row_ror:8 row_mask:0xf bank_mask:0xf
	v_mov_b32_dpp v151, v75 row_ror:8 row_mask:0xf bank_mask:0xf
	v_mov_b32_dpp v72, v76 row_ror:8 row_mask:0xf bank_mask:0x3
	v_mov_b32_dpp v73, v77 row_ror:8 row_mask:0xf bank_mask:0x3
	v_mov_b32_dpp v74, v78 row_ror:8 row_mask:0xf bank_mask:0x3
	v_mov_b32_dpp v75, v79 row_ror:8 row_mask:0xf bank_mask:0x3
	v_mov_b32_dpp v76, v148 quad_perm:[0,1,2,3] row_mask:0xf bank_mask:0xc
	v_mov_b32_dpp v77, v149 quad_perm:[0,1,2,3] row_mask:0xf bank_mask:0xc
	v_mov_b32_dpp v78, v150 quad_perm:[0,1,2,3] row_mask:0xf bank_mask:0xc
	v_mov_b32_dpp v79, v151 quad_perm:[0,1,2,3] row_mask:0xf bank_mask:0xc
	s_waitcnt vmcnt(27)
;     __device__ __forceinline__ void operator()(const f32x4 (&acc)[2][2][4][2], const pg8::Unit& u, int wr, int wc, int fr, int fq) const {
;     ...
;         for (int bj = 0; bj < 2; ++bj) {
;             const int col = u.pn * 256 + bj * 128 + wc * 32 + 8 * fq;
;             const f32x4 g0 = *(const f32x4*)(gp + col) * coef, g1 = *(const f32x4*)(gp + col + 4) * coef;
; #pragma unroll
;             for (int ai = 0; ai < 2; ++ai)
; #pragma unroll
;                 for (int m = 0; m < 4; ++m) {
;                     const size_t off = (size_t)(row0 + ai * 128 + m * 16) * DM + col;
;                     const f32x4 x0 = *(const f32x4*)(base + off), x1 = *(const f32x4*)(base + off + 4);
;                     *(f32x4*)(out + off) = x0 + g0 * acc[ai][bj][m][0]; *(f32x4*)(out + off + 4) = x1 + g1 * acc[ai][bj][m][1];
;                     if (m & 1) asm volatile("" ::: "memory");
;                 }
	v_pk_fma_f32 v[76:77], v[76:77], v[144:145], v[224:225]
	v_pk_fma_f32 v[78:79], v[78:79], v[146:147], v[226:227]
	v_pk_fma_f32 v[72:73], v[72:73], v[144:145], v[228:229]
	v_pk_fma_f32 v[74:75], v[74:75], v[146:147], v[230:231]
	s_add_u32 s98, s90, 0xa0000
	s_addc_u32 s99, s91, 0
	global_store_dwordx4 v240, v[76:79], s[98:99] sc1
	global_store_dwordx4 v242, v[72:75], s[98:99] sc1
	s_add_u32 s100, s90, 0xa0000
	s_addc_u32 s101, s91, 0
	global_load_dwordx4 v[224:227], v240, s[100:101] offset:512
	global_load_dwordx4 v[228:231], v242, s[100:101] offset:512
	v_mov_b32_dpp v148, v64 row_ror:8 row_mask:0xf bank_mask:0xf
	v_mov_b32_dpp v149, v65 row_ror:8 row_mask:0xf bank_mask:0xf
	v_mov_b32_dpp v150, v66 row_ror:8 row_mask:0xf bank_mask:0xf
	v_mov_b32_dpp v151, v67 row_ror:8 row_mask:0xf bank_mask:0xf
	v_mov_b32_dpp v64, v68 row_ror:8 row_mask:0xf bank_mask:0x3
	v_mov_b32_dpp v65, v69 row_ror:8 row_mask:0xf bank_mask:0x3
	v_mov_b32_dpp v66, v70 row_ror:8 row_mask:0xf bank_mask:0x3
	v_mov_b32_dpp v67, v71 row_ror:8 row_mask:0xf bank_mask:0x3
	v_mov_b32_dpp v68, v148 quad_perm:[0,1,2,3] row_mask:0xf bank_mask:0xc
	v_mov_b32_dpp v69, v149 quad_perm:[0,1,2,3] row_mask:0xf bank_mask:0xc
	v_mov_b32_dpp v70, v150 quad_perm:[0,1,2,3] row_mask:0xf bank_mask:0xc
	v_mov_b32_dpp v71, v151 quad_perm:[0,1,2,3] row_mask:0xf bank_mask:0xc
	s_waitcnt vmcnt(29)
	v_pk_fma_f32 v[68:69], v[68:69], v[144:145], v[232:233]
	v_pk_fma_f32 v[70:71], v[70:71], v[146:147], v[234:235]
	v_pk_fma_f32 v[64:65], v[64:65], v[144:145], v[236:237]
	v_pk_fma_f32 v[66:67], v[66:67], v[146:147], v[238:239]
	s_add_u32 s98, s90, 0xb0000
	s_addc_u32 s99, s91, 0
	global_store_dwordx4 v240, v[68:71], s[98:99] sc1
	global_store_dwordx4 v242, v[64:67], s[98:99] sc1
	s_add_u32 s100, s90, 0xb0000
	s_addc_u32 s101, s91, 0
	global_load_dwordx4 v[232:235], v240, s[100:101] offset:512
	global_load_dwordx4 v[236:239], v242, s[100:101] offset:512
	v_mov_b32_dpp v148, v56 row_ror:8 row_mask:0xf bank_mask:0xf
	v_mov_b32_dpp v149, v57 row_ror:8 row_mask:0xf bank_mask:0xf
	v_mov_b32_dpp v150, v58 row_ror:8 row_mask:0xf bank_mask:0xf
	v_mov_b32_dpp v151, v59 row_ror:8 row_mask:0xf bank_mask:0xf
	v_mov_b32_dpp v56, v60 row_ror:8 row_mask:0xf bank_mask:0x3
	v_mov_b32_dpp v57, v61 row_ror:8 row_mask:0xf bank_mask:0x3
	v_mov_b32_dpp v58, v62 row_ror:8 row_mask:0xf bank_mask:0x3
	v_mov_b32_dpp v59, v63 row_ror:8 row_mask:0xf bank_mask:0x3
	v_mov_b32_dpp v60, v148 quad_perm:[0,1,2,3] row_mask:0xf bank_mask:0xc
	v_mov_b32_dpp v61, v149 quad_perm:[0,1,2,3] row_mask:0xf bank_mask:0xc
	v_mov_b32_dpp v62, v150 quad_perm:[0,1,2,3] row_mask:0xf bank_mask:0xc
	v_mov_b32_dpp v63, v151 quad_perm:[0,1,2,3] row_mask:0xf bank_mask:0xc
	s_waitcnt vmcnt(28)
	v_pk_mul_f32 v[120:121], v[120:121], 0.5 op_sel_hi:[1,0]
	v_pk_mul_f32 v[122:123], v[122:123], 0.5 op_sel_hi:[1,0]
	v_pk_fma_f32 v[60:61], v[60:61], v[120:121], v[172:173]
	v_pk_fma_f32 v[62:63], v[62:63], v[122:123], v[174:175]
	v_pk_fma_f32 v[56:57], v[56:57], v[120:121], v[176:177]
	v_pk_fma_f32 v[58:59], v[58:59], v[122:123], v[178:179]
	s_add_u32 s98, s90, 0x0
	s_addc_u32 s99, s91, 0
	global_store_dwordx4 v240, v[60:63], s[98:99] offset:512 sc1
	global_store_dwordx4 v242, v[56:59], s[98:99] offset:512 sc1
	v_mov_b32_dpp v148, v48 row_ror:8 row_mask:0xf bank_mask:0xf
	v_mov_b32_dpp v149, v49 row_ror:8 row_mask:0xf bank_mask:0xf
	v_mov_b32_dpp v150, v50 row_ror:8 row_mask:0xf bank_mask:0xf
	v_mov_b32_dpp v151, v51 row_ror:8 row_mask:0xf bank_mask:0xf
	v_mov_b32_dpp v48, v52 row_ror:8 row_mask:0xf bank_mask:0x3
	v_mov_b32_dpp v49, v53 row_ror:8 row_mask:0xf bank_mask:0x3
	v_mov_b32_dpp v50, v54 row_ror:8 row_mask:0xf bank_mask:0x3
	v_mov_b32_dpp v51, v55 row_ror:8 row_mask:0xf bank_mask:0x3
	v_mov_b32_dpp v52, v148 quad_perm:[0,1,2,3] row_mask:0xf bank_mask:0xc
	v_mov_b32_dpp v53, v149 quad_perm:[0,1,2,3] row_mask:0xf bank_mask:0xc
	v_mov_b32_dpp v54, v150 quad_perm:[0,1,2,3] row_mask:0xf bank_mask:0xc
	v_mov_b32_dpp v55, v151 quad_perm:[0,1,2,3] row_mask:0xf bank_mask:0xc
	s_waitcnt vmcnt(26)
	v_pk_fma_f32 v[52:53], v[52:53], v[120:121], v[180:181]
	v_pk_fma_f32 v[54:55], v[54:55], v[122:123], v[182:183]
	v_pk_fma_f32 v[48:49], v[48:49], v[120:121], v[184:185]
	v_pk_fma_f32 v[50:51], v[50:51], v[122:123], v[186:187]
	s_add_u32 s98, s90, 0x10000
	s_addc_u32 s99, s91, 0
	global_store_dwordx4 v240, v[52:55], s[98:99] offset:512 sc1
	global_store_dwordx4 v242, v[48:51], s[98:99] offset:512 sc1
	v_mov_b32_dpp v148, v40 row_ror:8 row_mask:0xf bank_mask:0xf
	v_mov_b32_dpp v149, v41 row_ror:8 row_mask:0xf bank_mask:0xf
	v_mov_b32_dpp v150, v42 row_ror:8 row_mask:0xf bank_mask:0xf
	v_mov_b32_dpp v151, v43 row_ror:8 row_mask:0xf bank_mask:0xf
	v_mov_b32_dpp v40, v44 row_ror:8 row_mask:0xf bank_mask:0x3
	v_mov_b32_dpp v41, v45 row_ror:8 row_mask:0xf bank_mask:0x3
	v_mov_b32_dpp v42, v46 row_ror:8 row_mask:0xf bank_mask:0x3
	v_mov_b32_dpp v43, v47 row_ror:8 row_mask:0xf bank_mask:0x3
	v_mov_b32_dpp v44, v148 quad_perm:[0,1,2,3] row_mask:0xf bank_mask:0xc
	v_mov_b32_dpp v45, v149 quad_perm:[0,1,2,3] row_mask:0xf bank_mask:0xc
	v_mov_b32_dpp v46, v150 quad_perm:[0,1,2,3] row_mask:0xf bank_mask:0xc
	v_mov_b32_dpp v47, v151 quad_perm:[0,1,2,3] row_mask:0xf bank_mask:0xc
	s_waitcnt vmcnt(24)
; #define PG8_BAR __builtin_amdgcn_s_barrier()
; template <class Epi, class Sched, bool ALIGN_EPI = false, bool SP2 = false>
; __device__ __forceinline__ void gemm_phase(PG8_LAS unsigned char* lds, const Gemm g, const Sched& S, const Epi& E, const int wid) {
;     ...
;         if (!has_next) break;
; #pragma unroll
;         for (int a = 0; a < 2; ++a)
; #pragma unroll
;             for (int b = 0; b < 2; ++b)
; #pragma unroll
;                 for (int m = 0; m < 4; ++m)
; #pragma unroll
;                     for (int n = 0; n < 2; ++n) acc[a][b][m][n] = (f32x4){0.f, 0.f, 0.f, 0.f};
;         cur = nxt; cA = nA; cB = nB; ++ui;
;         if constexpr (ALIGN_EPI) { if (wr == 1) PG8_BAR; }
;     __device__ __forceinline__ void operator()(const f32x4 (&acc)[2][2][4][2], const pg8::Unit& u, int wr, int wc, int fr, int fq) const {
;     ...
;             for (int ai = 0; ai < 2; ++ai)
; #pragma unroll
;                 for (int m = 0; m < 4; ++m) {
;                     const size_t off = (size_t)(row0 + ai * 128 + m * 16) * DM + col;
;                     const f32x4 x0 = *(const f32x4*)(base + off), x1 = *(const f32x4*)(base + off + 4);
;                     *(f32x4*)(out + off) = x0 + g0 * acc[ai][bj][m][0]; *(f32x4*)(out + off + 4) = x1 + g1 * acc[ai][bj][m][1];
;                     if (m & 1) asm volatile("" ::: "memory");
;                 }
	v_pk_fma_f32 v[44:45], v[44:45], v[120:121], v[188:189]
	v_pk_fma_f32 v[46:47], v[46:47], v[122:123], v[190:191]
	v_pk_fma_f32 v[40:41], v[40:41], v[120:121], v[192:193]
	v_pk_fma_f32 v[42:43], v[42:43], v[122:123], v[194:195]
	s_add_u32 s98, s90, 0x20000
	s_addc_u32 s99, s91, 0
	global_store_dwordx4 v240, v[44:47], s[98:99] offset:512 sc1
	global_store_dwordx4 v242, v[40:43], s[98:99] offset:512 sc1
	v_mov_b32_dpp v148, v32 row_ror:8 row_mask:0xf bank_mask:0xf
	v_mov_b32_dpp v149, v33 row_ror:8 row_mask:0xf bank_mask:0xf
	v_mov_b32_dpp v150, v34 row_ror:8 row_mask:0xf bank_mask:0xf
	v_mov_b32_dpp v151, v35 row_ror:8 row_mask:0xf bank_mask:0xf
	v_mov_b32_dpp v32, v36 row_ror:8 row_mask:0xf bank_mask:0x3
	v_mov_b32_dpp v33, v37 row_ror:8 row_mask:0xf bank_mask:0x3
	v_mov_b32_dpp v34, v38 row_ror:8 row_mask:0xf bank_mask:0x3
	v_mov_b32_dpp v35, v39 row_ror:8 row_mask:0xf bank_mask:0x3
	v_mov_b32_dpp v36, v148 quad_perm:[0,1,2,3] row_mask:0xf bank_mask:0xc
	v_mov_b32_dpp v37, v149 quad_perm:[0,1,2,3] row_mask:0xf bank_mask:0xc
	v_mov_b32_dpp v38, v150 quad_perm:[0,1,2,3] row_mask:0xf bank_mask:0xc
	v_mov_b32_dpp v39, v151 quad_perm:[0,1,2,3] row_mask:0xf bank_mask:0xc
	s_waitcnt vmcnt(22)
	v_pk_fma_f32 v[36:37], v[36:37], v[120:121], v[196:197]
	v_pk_fma_f32 v[38:39], v[38:39], v[122:123], v[198:199]
	v_pk_fma_f32 v[32:33], v[32:33], v[120:121], v[200:201]
	v_pk_fma_f32 v[34:35], v[34:35], v[122:123], v[202:203]
	s_add_u32 s98, s90, 0x30000
	s_addc_u32 s99, s91, 0
	global_store_dwordx4 v240, v[36:39], s[98:99] offset:512 sc1
	global_store_dwordx4 v242, v[32:35], s[98:99] offset:512 sc1
	v_mov_b32_dpp v148, v24 row_ror:8 row_mask:0xf bank_mask:0xf
	v_mov_b32_dpp v149, v25 row_ror:8 row_mask:0xf bank_mask:0xf
	v_mov_b32_dpp v150, v26 row_ror:8 row_mask:0xf bank_mask:0xf
	v_mov_b32_dpp v151, v27 row_ror:8 row_mask:0xf bank_mask:0xf
	v_mov_b32_dpp v24, v28 row_ror:8 row_mask:0xf bank_mask:0x3
	v_mov_b32_dpp v25, v29 row_ror:8 row_mask:0xf bank_mask:0x3
	v_mov_b32_dpp v26, v30 row_ror:8 row_mask:0xf bank_mask:0x3
	v_mov_b32_dpp v27, v31 row_ror:8 row_mask:0xf bank_mask:0x3
	v_mov_b32_dpp v28, v148 quad_perm:[0,1,2,3] row_mask:0xf bank_mask:0xc
	v_mov_b32_dpp v29, v149 quad_perm:[0,1,2,3] row_mask:0xf bank_mask:0xc
	v_mov_b32_dpp v30, v150 quad_perm:[0,1,2,3] row_mask:0xf bank_mask:0xc
	v_mov_b32_dpp v31, v151 quad_perm:[0,1,2,3] row_mask:0xf bank_mask:0xc
	s_waitcnt vmcnt(20)
	v_pk_fma_f32 v[28:29], v[28:29], v[120:121], v[208:209]
	v_pk_fma_f32 v[30:31], v[30:31], v[122:123], v[210:211]
	v_pk_fma_f32 v[24:25], v[24:25], v[120:121], v[212:213]
	v_pk_fma_f32 v[26:27], v[26:27], v[122:123], v[214:215]
	s_add_u32 s98, s90, 0x80000
	s_addc_u32 s99, s91, 0
	global_store_dwordx4 v240, v[28:31], s[98:99] offset:512 sc1
	global_store_dwordx4 v242, v[24:27], s[98:99] offset:512 sc1
	v_mov_b32_dpp v148, v16 row_ror:8 row_mask:0xf bank_mask:0xf
	v_mov_b32_dpp v149, v17 row_ror:8 row_mask:0xf bank_mask:0xf
	v_mov_b32_dpp v150, v18 row_ror:8 row_mask:0xf bank_mask:0xf
	v_mov_b32_dpp v151, v19 row_ror:8 row_mask:0xf bank_mask:0xf
	v_mov_b32_dpp v16, v20 row_ror:8 row_mask:0xf bank_mask:0x3
	v_mov_b32_dpp v17, v21 row_ror:8 row_mask:0xf bank_mask:0x3
	v_mov_b32_dpp v18, v22 row_ror:8 row_mask:0xf bank_mask:0x3
	v_mov_b32_dpp v19, v23 row_ror:8 row_mask:0xf bank_mask:0x3
	v_mov_b32_dpp v20, v148 quad_perm:[0,1,2,3] row_mask:0xf bank_mask:0xc
	v_mov_b32_dpp v21, v149 quad_perm:[0,1,2,3] row_mask:0xf bank_mask:0xc
	v_mov_b32_dpp v22, v150 quad_perm:[0,1,2,3] row_mask:0xf bank_mask:0xc
	v_mov_b32_dpp v23, v151 quad_perm:[0,1,2,3] row_mask:0xf bank_mask:0xc
	s_waitcnt vmcnt(18)
	v_pk_fma_f32 v[20:21], v[20:21], v[120:121], v[216:217]
	v_pk_fma_f32 v[22:23], v[22:23], v[122:123], v[218:219]
	v_pk_fma_f32 v[16:17], v[16:17], v[120:121], v[220:221]
	v_pk_fma_f32 v[18:19], v[18:19], v[122:123], v[222:223]
	s_add_u32 s98, s90, 0x90000
	s_addc_u32 s99, s91, 0
	global_store_dwordx4 v240, v[20:23], s[98:99] offset:512 sc1
	global_store_dwordx4 v242, v[16:19], s[98:99] offset:512 sc1
	v_mov_b32_dpp v148, v8 row_ror:8 row_mask:0xf bank_mask:0xf
	v_mov_b32_dpp v149, v9 row_ror:8 row_mask:0xf bank_mask:0xf
	v_mov_b32_dpp v150, v10 row_ror:8 row_mask:0xf bank_mask:0xf
	v_mov_b32_dpp v151, v11 row_ror:8 row_mask:0xf bank_mask:0xf
	v_mov_b32_dpp v8, v12 row_ror:8 row_mask:0xf bank_mask:0x3
	v_mov_b32_dpp v9, v13 row_ror:8 row_mask:0xf bank_mask:0x3
	v_mov_b32_dpp v10, v14 row_ror:8 row_mask:0xf bank_mask:0x3
	v_mov_b32_dpp v11, v15 row_ror:8 row_mask:0xf bank_mask:0x3
	v_mov_b32_dpp v12, v148 quad_perm:[0,1,2,3] row_mask:0xf bank_mask:0xc
	v_mov_b32_dpp v13, v149 quad_perm:[0,1,2,3] row_mask:0xf bank_mask:0xc
	v_mov_b32_dpp v14, v150 quad_perm:[0,1,2,3] row_mask:0xf bank_mask:0xc
	v_mov_b32_dpp v15, v151 quad_perm:[0,1,2,3] row_mask:0xf bank_mask:0xc
	s_waitcnt vmcnt(16)
	v_pk_fma_f32 v[12:13], v[12:13], v[120:121], v[224:225]
	v_pk_fma_f32 v[14:15], v[14:15], v[122:123], v[226:227]
	v_pk_fma_f32 v[8:9], v[8:9], v[120:121], v[228:229]
	v_pk_fma_f32 v[10:11], v[10:11], v[122:123], v[230:231]
	s_add_u32 s98, s90, 0xa0000
	s_addc_u32 s99, s91, 0
	global_store_dwordx4 v240, v[12:15], s[98:99] offset:512 sc1
	global_store_dwordx4 v242, v[8:11], s[98:99] offset:512 sc1
	v_mov_b32_dpp v148, v0 row_ror:8 row_mask:0xf bank_mask:0xf
	v_mov_b32_dpp v149, v1 row_ror:8 row_mask:0xf bank_mask:0xf
	v_mov_b32_dpp v150, v2 row_ror:8 row_mask:0xf bank_mask:0xf
	v_mov_b32_dpp v151, v3 row_ror:8 row_mask:0xf bank_mask:0xf
	v_mov_b32_dpp v0, v4 row_ror:8 row_mask:0xf bank_mask:0x3
	v_mov_b32_dpp v1, v5 row_ror:8 row_mask:0xf bank_mask:0x3
	v_mov_b32_dpp v2, v6 row_ror:8 row_mask:0xf bank_mask:0x3
	v_mov_b32_dpp v3, v7 row_ror:8 row_mask:0xf bank_mask:0x3
	v_mov_b32_dpp v4, v148 quad_perm:[0,1,2,3] row_mask:0xf bank_mask:0xc
	v_mov_b32_dpp v5, v149 quad_perm:[0,1,2,3] row_mask:0xf bank_mask:0xc
	v_mov_b32_dpp v6, v150 quad_perm:[0,1,2,3] row_mask:0xf bank_mask:0xc
	v_mov_b32_dpp v7, v151 quad_perm:[0,1,2,3] row_mask:0xf bank_mask:0xc
	s_waitcnt vmcnt(14)
	v_pk_fma_f32 v[4:5], v[4:5], v[120:121], v[232:233]
	v_pk_fma_f32 v[6:7], v[6:7], v[122:123], v[234:235]
	v_pk_fma_f32 v[0:1], v[0:1], v[120:121], v[236:237]
	v_pk_fma_f32 v[2:3], v[2:3], v[122:123], v[238:239]
	s_add_u32 s98, s90, 0xb0000
	s_addc_u32 s99, s91, 0
	global_store_dwordx4 v240, v[4:7], s[98:99] offset:512 sc1
	global_store_dwordx4 v242, v[0:3], s[98:99] offset:512 sc1
	s_and_b64 vcc, exec, s[0:1]
	s_mov_b64 s[0:1], -1
	s_cbranch_vccnz .LBB0_1381
	s_andn2_b64 vcc, exec, s[6:7]
	s_cbranch_vccnz .LBB0_1380
	s_barrier
	s_branch .LBB0_1380
